# QKV epilogue load-ahead: each row group's cos/sin rows requested right behind its ssq load (into v246-v253) instead of after the statistics and shuffles; ssq wait counted vmcnt(2)
# speedup vs baseline: 1.0049x; 1.0049x over previous
; __device__ __forceinline__ u32x4 pack8(const f32x4 a, const f32x4 b) { u32x4 w; w.x = cvt_pk_bf16(a[0], a[1]); w.y = cvt_pk_bf16(a[2], a[3]); w.z = cvt_pk_bf16(b[0], b[1]); w.w = cvt_pk_bf16(b[2], b[3]); return w; }
;     __device__ __forceinline__ void operator()(const f32x4 (&acc)[2][2][4][2], const Unit& u, int wr, int wc, int fr, int fq) const {
;     ...
;             f32x4 gv[2][2], cs[2][2];
; #pragma unroll
;             for (int bj = 0; bj < 2; ++bj)
; #pragma unroll
;                 for (int n = 0; n < 2; ++n) { gv[bj][n] = *(const f32x4*)(gp + 32 * bj + 8 * fq + 4 * n); cs[bj][n] = (f32x4){0.f, 0.f, 0.f, 0.f}; }
; #pragma unroll
;             for (int ai = 0; ai < 2; ++ai)
; #pragma unroll
;                 for (int m = 0; m < 4; ++m) { if (m == 0) asm volatile("" ::: "memory"); const int row = row0 + ai * HALF + m * 16; const float rs = rstd_of(ssq, row);
;                     f32x4 v[2][2]; float ss = 0.f;
; #pragma unroll
;                     for (int bj = 0; bj < 2; ++bj)
; #pragma unroll
;                         for (int n = 0; n < 2; ++n) { v[bj][n] = acc[ai][bj][m][n] * rs; const f32x4 q = v[bj][n] * v[bj][n]; ss += (q[0] + q[1]) + (q[2] + q[3]); }
;                     ss += __shfl_xor(ss, 16); ss += __shfl_xor(ss, 32);
;                     const float rn = __builtin_amdgcn_rsqf(ss * (1.0f / 64.0f) + 1e-6f);
;                     f32x4 o[2][2];
; #pragma unroll
;                     for (int n = 0; n < 2; ++n) { const f32x4 c = *(const f32x4*)(cosT + (size_t)row * 32 + 8 * fq + 4 * n), s = *(const f32x4*)(sinT + (size_t)row * 32 + 8 * fq + 4 * n);
;                         const f32x4 y1 = v[0][n] * rn * gv[0][n], y2 = v[1][n] * rn * gv[1][n];
;                         o[0][n] = y1 * c - y2 * s; o[1][n] = y2 * c + y1 * s; }
;                     if (dok) {
; #pragma unroll
;                         for (int bj = 0; bj < 2; ++bj)
; #pragma unroll
;                             for (int n = 0; n < 2; ++n) cs[bj][n] = cs[bj][n] + o[bj][n]; }
; #pragma unroll
;                     for (int bj = 0; bj < 2; ++bj) *(u32x4*)(ob + (size_t)row * 2816 + 32 * bj) = pack8(o[bj][0] * osc, o[bj][1] * osc); }
.LBB0_415:
	s_lshl_b32 s80, s1, 6
	s_ashr_i32 s81, s80, 31
	v_lshl_add_u32 v182, s78, 8, v204
	v_lshl_add_u64 v[180:181], s[80:81], 1, v[168:169]
	s_mov_b64 s[14:15], -1
	s_andn2_b64 vcc, exec, s[10:11]
	v_ashrrev_i32_e32 v183, 31, v182
	s_cbranch_vccz .LBB0_438
	global_load_dwordx4 v[136:139], v207, s[12:13] offset:16
	global_load_dwordx4 v[144:147], v207, s[12:13]
	global_load_dwordx4 v[132:135], v207, s[12:13] offset:144
	global_load_dwordx4 v[140:143], v207, s[12:13] offset:128
	v_lshl_add_u64 v[114:115], v[182:183], 4, s[18:19]
	flat_load_dwordx4 v[148:151], v[114:115]
	v_lshlrev_b64 v[250:251], 7, v[182:183]
	v_lshl_add_u64 v[246:247], v[170:171], 0, v[250:251]
	v_lshl_add_u64 v[250:251], v[172:173], 0, v[250:251]
	global_load_dwordx4 v[246:249], v[246:247], off
	global_load_dwordx4 v[250:253], v[250:251], off
	s_waitcnt vmcnt(2) lgkmcnt(0)
	v_mov_b32_e32 v114, v149
	v_mov_b32_e32 v115, v150
	v_mov_b32_e32 v149, v151
	v_pk_add_f32 v[114:115], v[114:115], v[148:149]
	s_nop 0
	v_add_f32_e32 v112, v114, v115
	v_fmamk_f32 v112, v112, 0x3a800000, v231
	v_rsq_f32_e32 v112, v112
	s_nop 0
	v_pk_mul_f32 v[154:155], v[128:129], v[112:113] op_sel_hi:[1,0]
	v_pk_mul_f32 v[156:157], v[130:131], v[112:113] op_sel_hi:[1,0]
	v_pk_mul_f32 v[148:149], v[154:155], v[154:155]
	v_pk_mul_f32 v[114:115], v[156:157], v[156:157]
	v_pk_mul_f32 v[160:161], v[122:123], v[112:113] op_sel_hi:[1,0]
	v_pk_mov_b32 v[150:151], v[148:149], v[114:115] op_sel:[1,0]
	v_mov_b32_e32 v149, v115
	v_pk_add_f32 v[114:115], v[150:151], v[148:149]
	v_pk_mul_f32 v[148:149], v[126:127], v[112:113] op_sel_hi:[1,0]
	v_pk_add_f32 v[162:163], v[114:115], v[114:115] op_sel_hi:[0,1]
	v_pk_mul_f32 v[114:115], v[124:125], v[112:113] op_sel_hi:[1,0]
	v_pk_mul_f32 v[150:151], v[148:149], v[148:149]
	v_pk_mul_f32 v[152:153], v[114:115], v[114:115]
	s_nop 0
	v_pk_mov_b32 v[158:159], v[152:153], v[150:151] op_sel:[1,0]
	v_mov_b32_e32 v153, v151
	v_pk_add_f32 v[150:151], v[158:159], v[152:153]
	v_pk_mul_f32 v[158:159], v[120:121], v[112:113] op_sel_hi:[1,0]
	v_pk_add_f32 v[186:187], v[150:151], v[150:151] op_sel_hi:[0,1]
	v_pk_mul_f32 v[150:151], v[160:161], v[160:161]
	v_pk_mul_f32 v[152:153], v[158:159], v[158:159]
	v_add_f32_e32 v191, v150, v151
	v_add_f32_e32 v189, v152, v153
	v_pk_mul_f32 v[150:151], v[116:117], v[112:113] op_sel_hi:[1,0]
	v_pk_mul_f32 v[152:153], v[118:119], v[112:113] op_sel_hi:[1,0]
	v_pk_mul_f32 v[194:195], v[150:151], v[150:151]
	v_pk_mul_f32 v[192:193], v[152:153], v[152:153]
	v_mov_b32_e32 v188, v194
	v_mov_b32_e32 v190, v195
	v_mov_b32_e32 v162, v192
	v_mov_b32_e32 v186, v193
	v_pk_add_f32 v[188:189], v[188:189], v[190:191]
	v_pk_add_f32 v[162:163], v[162:163], v[186:187]
	s_nop 0
	v_pk_add_f32 v[162:163], v[188:189], v[162:163]
	s_nop 0
	v_add_f32_e32 v112, v162, v163
	v_and_b32_e32 v163, 64, v236
	v_xor_b32_e32 v162, 16, v236
	v_add_u32_e32 v208, 64, v163
	v_cmp_lt_i32_e32 vcc, v162, v208
	s_nop 1
	v_cndmask_b32_e32 v162, v236, v162, vcc
	v_lshlrev_b32_e32 v209, 2, v162
	ds_bpermute_b32 v162, v209, v112
	s_waitcnt lgkmcnt(0)
	v_add_f32_e32 v112, v112, v162
	v_xor_b32_e32 v162, 32, v236
	v_cmp_lt_i32_e32 vcc, v162, v208
	s_nop 1
	v_cndmask_b32_e32 v162, v236, v162, vcc
	v_lshlrev_b32_e32 v222, 2, v162
	ds_bpermute_b32 v162, v222, v112
	s_and_b64 vcc, exec, s[82:83]
	s_waitcnt lgkmcnt(0)
	v_add_f32_e32 v112, v112, v162
	v_lshlrev_b64 v[162:163], 7, v[182:183]
	v_lshl_add_u64 v[198:199], v[170:171], 0, v[162:163]
	v_lshl_add_u64 v[162:163], v[172:173], 0, v[162:163]
	s_waitcnt vmcnt(0)
	v_mov_b64_e32 v[186:187], v[246:247]
	v_mov_b64_e32 v[188:189], v[248:249]
	v_mov_b64_e32 v[194:195], v[250:251]
	v_mov_b64_e32 v[196:197], v[252:253]
	v_fmamk_f32 v112, v112, 0x3c800000, v231
	v_rsq_f32_e32 v112, v112
	s_nop 0
	v_pk_mul_f32 v[158:159], v[158:159], v[112:113] op_sel_hi:[1,0]
	v_pk_mul_f32 v[160:161], v[160:161], v[112:113] op_sel_hi:[1,0]
	v_pk_mul_f32 v[156:157], v[156:157], v[112:113] op_sel_hi:[1,0]
	v_pk_mul_f32 v[154:155], v[154:155], v[112:113] op_sel_hi:[1,0]
	v_pk_mul_f32 v[160:161], v[142:143], v[160:161]
	v_pk_mul_f32 v[158:159], v[140:141], v[158:159]
	v_pk_mul_f32 v[154:155], v[144:145], v[154:155]
	v_pk_mul_f32 v[156:157], v[146:147], v[156:157]
	v_pk_mul_f32 v[150:151], v[150:151], v[112:113] op_sel_hi:[1,0]
	v_pk_mul_f32 v[152:153], v[152:153], v[112:113] op_sel_hi:[1,0]
	v_pk_mul_f32 v[148:149], v[148:149], v[112:113] op_sel_hi:[1,0]
	v_pk_mul_f32 v[114:115], v[114:115], v[112:113] op_sel_hi:[1,0]
	v_pk_mul_f32 v[152:153], v[134:135], v[152:153]
	v_pk_mul_f32 v[150:151], v[132:133], v[150:151]
	v_pk_mul_f32 v[114:115], v[136:137], v[114:115]
	v_pk_mul_f32 v[148:149], v[138:139], v[148:149]
	s_waitcnt vmcnt(0) lgkmcnt(0)
	v_pk_mul_f32 v[192:193], v[194:195], v[158:159]
	v_pk_mul_f32 v[190:191], v[196:197], v[160:161]
	v_pk_mul_f32 v[158:159], v[186:187], v[158:159]
	v_pk_mul_f32 v[160:161], v[188:189], v[160:161]
	v_pk_fma_f32 v[190:191], v[188:189], v[156:157], v[190:191] neg_lo:[0,0,1] neg_hi:[0,0,1]
	v_pk_fma_f32 v[192:193], v[186:187], v[154:155], v[192:193] neg_lo:[0,0,1] neg_hi:[0,0,1]
	v_pk_fma_f32 v[186:187], v[196:197], v[156:157], v[160:161]
	v_pk_fma_f32 v[188:189], v[194:195], v[154:155], v[158:159]
	flat_load_dwordx4 v[154:157], v[198:199] offset:16
	flat_load_dwordx4 v[158:161], v[162:163] offset:16
	s_waitcnt vmcnt(0) lgkmcnt(0)
	v_pk_mul_f32 v[162:163], v[158:159], v[150:151]
	v_pk_mul_f32 v[194:195], v[160:161], v[152:153]
	v_pk_mul_f32 v[150:151], v[154:155], v[150:151]
	v_pk_mul_f32 v[152:153], v[156:157], v[152:153]
	v_pk_fma_f32 v[198:199], v[156:157], v[148:149], v[194:195] neg_lo:[0,0,1] neg_hi:[0,0,1]
	v_pk_fma_f32 v[200:201], v[154:155], v[114:115], v[162:163] neg_lo:[0,0,1] neg_hi:[0,0,1]
	v_pk_fma_f32 v[194:195], v[160:161], v[148:149], v[152:153]
	v_pk_fma_f32 v[196:197], v[158:159], v[114:115], v[150:151]
	s_cbranch_vccz .LBB0_418
	v_pk_add_f32 v[162:163], v[190:191], 0 op_sel_hi:[1,0]
	v_pk_add_f32 v[160:161], v[192:193], 0 op_sel_hi:[1,0]
	v_pk_add_f32 v[158:159], v[198:199], 0 op_sel_hi:[1,0]
	v_pk_add_f32 v[156:157], v[200:201], 0 op_sel_hi:[1,0]
	v_pk_add_f32 v[154:155], v[186:187], 0 op_sel_hi:[1,0]
	v_pk_add_f32 v[152:153], v[188:189], 0 op_sel_hi:[1,0]
	v_pk_add_f32 v[150:151], v[194:195], 0 op_sel_hi:[1,0]
	v_pk_add_f32 v[148:149], v[196:197], 0 op_sel_hi:[1,0]
	s_branch .LBB0_419

; __device__ __forceinline__ u32x4 pack8(const f32x4 a, const f32x4 b) { u32x4 w; w.x = cvt_pk_bf16(a[0], a[1]); w.y = cvt_pk_bf16(a[2], a[3]); w.z = cvt_pk_bf16(b[0], b[1]); w.w = cvt_pk_bf16(b[2], b[3]); return w; }
;     __device__ __forceinline__ void operator()(const f32x4 (&acc)[2][2][4][2], const Unit& u, int wr, int wc, int fr, int fq) const {
;     ...
;                 for (int m = 0; m < 4; ++m) { if (m == 0) asm volatile("" ::: "memory"); const int row = row0 + ai * HALF + m * 16; const float rs = rstd_of(ssq, row);
;                     f32x4 v[2][2]; float ss = 0.f;
; #pragma unroll
;                     for (int bj = 0; bj < 2; ++bj)
; #pragma unroll
;                         for (int n = 0; n < 2; ++n) { v[bj][n] = acc[ai][bj][m][n] * rs; const f32x4 q = v[bj][n] * v[bj][n]; ss += (q[0] + q[1]) + (q[2] + q[3]); }
;                     ss += __shfl_xor(ss, 16); ss += __shfl_xor(ss, 32);
;                     const float rn = __builtin_amdgcn_rsqf(ss * (1.0f / 64.0f) + 1e-6f);
;                     f32x4 o[2][2];
; #pragma unroll
;                     for (int n = 0; n < 2; ++n) { const f32x4 c = *(const f32x4*)(cosT + (size_t)row * 32 + 8 * fq + 4 * n), s = *(const f32x4*)(sinT + (size_t)row * 32 + 8 * fq + 4 * n);
;                         const f32x4 y1 = v[0][n] * rn * gv[0][n], y2 = v[1][n] * rn * gv[1][n];
;                         o[0][n] = y1 * c - y2 * s; o[1][n] = y2 * c + y1 * s; }
;                     if (dok) {
; #pragma unroll
;                         for (int bj = 0; bj < 2; ++bj)
; #pragma unroll
;                             for (int n = 0; n < 2; ++n) cs[bj][n] = cs[bj][n] + o[bj][n]; }
; #pragma unroll
;                     for (int bj = 0; bj < 2; ++bj) *(u32x4*)(ob + (size_t)row * 2816 + 32 * bj) = pack8(o[bj][0] * osc, o[bj][1] * osc); }
.LBB0_419:
	v_pk_mul_f32 v[202:203], v[184:185], v[190:191] op_sel_hi:[0,1]
	v_pk_mul_f32 v[190:191], v[184:185], v[192:193] op_sel_hi:[0,1]
	v_pk_mul_f32 v[198:199], v[184:185], v[198:199] op_sel_hi:[0,1]
	v_pk_mul_f32 v[192:193], v[184:185], v[200:201] op_sel_hi:[0,1]
	v_mad_i64_i32 v[114:115], s[10:11], v182, s92, v[180:181]
	v_cvt_pk_bf16_f32 v190, v190, v191
	v_cvt_pk_bf16_f32 v191, v202, v203
	v_cvt_pk_bf16_f32 v192, v192, v193
	v_cvt_pk_bf16_f32 v193, v198, v199
	flat_store_dwordx4 v[114:115], v[190:193]
	s_andn2_b64 vcc, exec, s[82:83]
	s_nop 0
	v_pk_mul_f32 v[190:191], v[184:185], v[186:187] op_sel_hi:[0,1]
	v_pk_mul_f32 v[186:187], v[184:185], v[188:189] op_sel_hi:[0,1]
	v_pk_mul_f32 v[192:193], v[184:185], v[194:195] op_sel_hi:[0,1]
	v_pk_mul_f32 v[188:189], v[184:185], v[196:197] op_sel_hi:[0,1]
	v_cvt_pk_bf16_f32 v186, v186, v187
	v_cvt_pk_bf16_f32 v187, v190, v191
	v_cvt_pk_bf16_f32 v188, v188, v189
	v_cvt_pk_bf16_f32 v189, v192, v193
	flat_store_dwordx4 v[114:115], v[186:189] offset:64
	v_or_b32_e32 v114, 16, v182
	v_ashrrev_i32_e32 v115, 31, v114
	v_lshl_add_u64 v[186:187], v[114:115], 4, s[18:19]
	flat_load_dwordx4 v[186:189], v[186:187]
	v_lshlrev_b64 v[250:251], 7, v[114:115]
	v_lshl_add_u64 v[246:247], v[170:171], 0, v[250:251]
	v_lshl_add_u64 v[250:251], v[172:173], 0, v[250:251]
	global_load_dwordx4 v[246:249], v[246:247], off
	global_load_dwordx4 v[250:253], v[250:251], off
	s_waitcnt vmcnt(2) lgkmcnt(0)
	v_mov_b32_e32 v190, v187
	v_mov_b32_e32 v191, v188
	v_mov_b32_e32 v187, v189
	v_pk_add_f32 v[186:187], v[190:191], v[186:187]
	s_nop 0
	v_add_f32_e32 v112, v186, v187
	v_fmamk_f32 v112, v112, 0x3a800000, v231
	v_rsq_f32_e32 v112, v112
	s_nop 0
	v_pk_mul_f32 v[190:191], v[108:109], v[112:113] op_sel_hi:[1,0]
	v_pk_mul_f32 v[192:193], v[110:111], v[112:113] op_sel_hi:[1,0]
	v_pk_mul_f32 v[188:189], v[190:191], v[190:191]
	v_pk_mul_f32 v[186:187], v[192:193], v[192:193]
	v_pk_mul_f32 v[196:197], v[106:107], v[112:113] op_sel_hi:[1,0]
	v_pk_mov_b32 v[194:195], v[188:189], v[186:187] op_sel:[1,0]
	v_mov_b32_e32 v189, v187
	v_pk_add_f32 v[186:187], v[194:195], v[188:189]
	v_pk_mul_f32 v[194:195], v[104:105], v[112:113] op_sel_hi:[1,0]
	v_pk_mul_f32 v[188:189], v[196:197], v[196:197]
	v_pk_mul_f32 v[198:199], v[194:195], v[194:195]
	v_pk_mul_f32 v[202:203], v[100:101], v[112:113] op_sel_hi:[1,0]
	v_pk_mov_b32 v[200:201], v[198:199], v[188:189] op_sel:[1,0]
	v_mov_b32_e32 v199, v189
	v_pk_mul_f32 v[224:225], v[102:103], v[112:113] op_sel_hi:[1,0]
	v_pk_add_f32 v[188:189], v[200:201], v[198:199]
	v_pk_mul_f32 v[198:199], v[224:225], v[224:225]
	v_pk_mul_f32 v[200:201], v[202:203], v[202:203]
	v_add_f32_e32 v213, v198, v199
	v_add_f32_e32 v211, v200, v201
	v_pk_mul_f32 v[198:199], v[96:97], v[112:113] op_sel_hi:[1,0]
	v_pk_mul_f32 v[200:201], v[98:99], v[112:113] op_sel_hi:[1,0]
	v_pk_add_f32 v[186:187], v[186:187], v[186:187] op_sel_hi:[0,1]
	v_pk_add_f32 v[188:189], v[188:189], v[188:189] op_sel_hi:[0,1]
	v_pk_mul_f32 v[226:227], v[200:201], v[200:201]
	v_pk_mul_f32 v[228:229], v[198:199], v[198:199]
	v_mov_b32_e32 v186, v226
	v_mov_b32_e32 v210, v228
	v_mov_b32_e32 v212, v229
	v_mov_b32_e32 v188, v227
	v_pk_add_f32 v[210:211], v[210:211], v[212:213]
	v_pk_add_f32 v[186:187], v[186:187], v[188:189]
	s_nop 0
	v_pk_add_f32 v[186:187], v[210:211], v[186:187]
	s_nop 0
	v_add_f32_e32 v112, v186, v187
	v_lshlrev_b64 v[186:187], 7, v[114:115]
	v_lshl_add_u64 v[226:227], v[170:171], 0, v[186:187]
	v_lshl_add_u64 v[228:229], v[172:173], 0, v[186:187]
	s_waitcnt vmcnt(0)
	v_mov_b64_e32 v[186:187], v[246:247]
	v_mov_b64_e32 v[188:189], v[248:249]
	v_mov_b64_e32 v[210:211], v[250:251]
	v_mov_b64_e32 v[212:213], v[252:253]
	ds_bpermute_b32 v185, v209, v112
	s_waitcnt lgkmcnt(0)
	v_add_f32_e32 v112, v112, v185
	ds_bpermute_b32 v185, v222, v112
	s_waitcnt lgkmcnt(0)
	v_add_f32_e32 v112, v112, v185
	v_fmamk_f32 v112, v112, 0x3c800000, v231
	v_rsq_f32_e32 v112, v112
	s_nop 0
	v_pk_mul_f32 v[190:191], v[190:191], v[112:113] op_sel_hi:[1,0]
	v_pk_mul_f32 v[192:193], v[192:193], v[112:113] op_sel_hi:[1,0]
	v_pk_mul_f32 v[232:233], v[144:145], v[190:191]
	v_pk_mul_f32 v[190:191], v[202:203], v[112:113] op_sel_hi:[1,0]
	v_pk_mul_f32 v[242:243], v[146:147], v[192:193]
	v_pk_mul_f32 v[192:193], v[224:225], v[112:113] op_sel_hi:[1,0]
	v_pk_mul_f32 v[224:225], v[140:141], v[190:191]
	v_pk_mul_f32 v[202:203], v[142:143], v[192:193]
	v_pk_mul_f32 v[196:197], v[196:197], v[112:113] op_sel_hi:[1,0]
	v_pk_mul_f32 v[194:195], v[194:195], v[112:113] op_sel_hi:[1,0]
	s_waitcnt vmcnt(0)
	v_pk_mul_f32 v[192:193], v[210:211], v[224:225]
	v_pk_mul_f32 v[190:191], v[212:213], v[202:203]
	v_pk_fma_f32 v[192:193], v[186:187], v[232:233], v[192:193] neg_lo:[0,0,1] neg_hi:[0,0,1]
	v_pk_mul_f32 v[224:225], v[186:187], v[224:225]
	v_pk_mul_f32 v[186:187], v[188:189], v[202:203]
	v_pk_fma_f32 v[190:191], v[188:189], v[242:243], v[190:191] neg_lo:[0,0,1] neg_hi:[0,0,1]
	v_pk_fma_f32 v[186:187], v[212:213], v[242:243], v[186:187]
	v_pk_fma_f32 v[188:189], v[210:211], v[232:233], v[224:225]
	flat_load_dwordx4 v[210:213], v[226:227] offset:16
	s_nop 0
	flat_load_dwordx4 v[224:227], v[228:229] offset:16
	v_pk_mul_f32 v[202:203], v[136:137], v[194:195]
	v_pk_mul_f32 v[194:195], v[138:139], v[196:197]
	v_pk_mul_f32 v[196:197], v[198:199], v[112:113] op_sel_hi:[1,0]
	v_pk_mul_f32 v[198:199], v[200:201], v[112:113] op_sel_hi:[1,0]
	v_pk_mul_f32 v[196:197], v[132:133], v[196:197]
	v_pk_mul_f32 v[228:229], v[134:135], v[198:199]
	v_cndmask_b32_e64 v112, 0, 1, s[82:83]
	v_cmp_ne_u32_e64 s[10:11], 1, v112
	s_waitcnt vmcnt(0) lgkmcnt(0)
	v_pk_mul_f32 v[200:201], v[224:225], v[196:197]
	v_pk_mul_f32 v[198:199], v[226:227], v[228:229]
	v_pk_fma_f32 v[200:201], v[210:211], v[202:203], v[200:201] neg_lo:[0,0,1] neg_hi:[0,0,1]
	v_pk_mul_f32 v[196:197], v[210:211], v[196:197]
	v_pk_mul_f32 v[210:211], v[212:213], v[228:229]
	v_pk_fma_f32 v[198:199], v[212:213], v[194:195], v[198:199] neg_lo:[0,0,1] neg_hi:[0,0,1]
	v_pk_fma_f32 v[194:195], v[226:227], v[194:195], v[210:211]
	v_pk_fma_f32 v[196:197], v[224:225], v[202:203], v[196:197]
	s_cbranch_vccnz .LBB0_421
	v_pk_add_f32 v[162:163], v[162:163], v[190:191]
	v_pk_add_f32 v[160:161], v[160:161], v[192:193]
	v_pk_add_f32 v[158:159], v[158:159], v[198:199]
	v_pk_add_f32 v[156:157], v[156:157], v[200:201]
	v_pk_add_f32 v[154:155], v[154:155], v[186:187]
	v_pk_add_f32 v[152:153], v[152:153], v[188:189]
	v_pk_add_f32 v[150:151], v[150:151], v[194:195]
	v_pk_add_f32 v[148:149], v[148:149], v[196:197]
; __device__ __forceinline__ u32x4 pack8(const f32x4 a, const f32x4 b) { u32x4 w; w.x = cvt_pk_bf16(a[0], a[1]); w.y = cvt_pk_bf16(a[2], a[3]); w.z = cvt_pk_bf16(b[0], b[1]); w.w = cvt_pk_bf16(b[2], b[3]); return w; }
;     __device__ __forceinline__ void operator()(const f32x4 (&acc)[2][2][4][2], const Unit& u, int wr, int wc, int fr, int fq) const {
;     ...
;                 for (int m = 0; m < 4; ++m) { if (m == 0) asm volatile("" ::: "memory"); const int row = row0 + ai * HALF + m * 16; const float rs = rstd_of(ssq, row);
;                     f32x4 v[2][2]; float ss = 0.f;
; #pragma unroll
;                     for (int bj = 0; bj < 2; ++bj)
; #pragma unroll
;                         for (int n = 0; n < 2; ++n) { v[bj][n] = acc[ai][bj][m][n] * rs; const f32x4 q = v[bj][n] * v[bj][n]; ss += (q[0] + q[1]) + (q[2] + q[3]); }
;                     ss += __shfl_xor(ss, 16); ss += __shfl_xor(ss, 32);
;                     const float rn = __builtin_amdgcn_rsqf(ss * (1.0f / 64.0f) + 1e-6f);
;                     f32x4 o[2][2];
; #pragma unroll
;                     for (int n = 0; n < 2; ++n) { const f32x4 c = *(const f32x4*)(cosT + (size_t)row * 32 + 8 * fq + 4 * n), s = *(const f32x4*)(sinT + (size_t)row * 32 + 8 * fq + 4 * n);
;                         const f32x4 y1 = v[0][n] * rn * gv[0][n], y2 = v[1][n] * rn * gv[1][n];
;                         o[0][n] = y1 * c - y2 * s; o[1][n] = y2 * c + y1 * s; }
;                     if (dok) {
; #pragma unroll
;                         for (int bj = 0; bj < 2; ++bj)
; #pragma unroll
;                             for (int n = 0; n < 2; ++n) cs[bj][n] = cs[bj][n] + o[bj][n]; }
; #pragma unroll
;                     for (int bj = 0; bj < 2; ++bj) *(u32x4*)(ob + (size_t)row * 2816 + 32 * bj) = pack8(o[bj][0] * osc, o[bj][1] * osc); }
.LBB0_421:
	v_mov_b32_e32 v185, v184
	v_mad_i64_i32 v[202:203], s[12:13], v114, s92, v[180:181]
	v_mov_b32_e32 v114, v184
	v_mov_b32_e32 v115, v184
	v_pk_mul_f32 v[210:211], v[114:115], v[190:191]
	v_pk_mul_f32 v[190:191], v[184:185], v[192:193]
	v_pk_mul_f32 v[198:199], v[114:115], v[198:199]
	v_pk_mul_f32 v[192:193], v[184:185], v[200:201]
	v_cvt_pk_bf16_f32 v190, v190, v191
	v_cvt_pk_bf16_f32 v191, v210, v211
	v_cvt_pk_bf16_f32 v192, v192, v193
	v_cvt_pk_bf16_f32 v193, v198, v199
	flat_store_dwordx4 v[202:203], v[190:193]
	s_and_b64 vcc, exec, s[10:11]
	s_nop 0
	v_pk_mul_f32 v[190:191], v[114:115], v[186:187]
	v_pk_mul_f32 v[186:187], v[184:185], v[188:189]
	v_pk_mul_f32 v[192:193], v[114:115], v[194:195]
	v_pk_mul_f32 v[188:189], v[184:185], v[196:197]
	v_cvt_pk_bf16_f32 v186, v186, v187
	v_cvt_pk_bf16_f32 v187, v190, v191
	v_cvt_pk_bf16_f32 v188, v188, v189
	v_cvt_pk_bf16_f32 v189, v192, v193
	flat_store_dwordx4 v[202:203], v[186:189] offset:64
	s_nop 1
	v_or_b32_e32 v186, 32, v182
	v_ashrrev_i32_e32 v187, 31, v186
	v_lshl_add_u64 v[188:189], v[186:187], 4, s[18:19]
	flat_load_dwordx4 v[188:191], v[188:189]
	v_lshlrev_b64 v[250:251], 7, v[186:187]
	v_lshl_add_u64 v[246:247], v[170:171], 0, v[250:251]
	v_lshl_add_u64 v[250:251], v[172:173], 0, v[250:251]
	global_load_dwordx4 v[246:249], v[246:247], off
	global_load_dwordx4 v[250:253], v[250:251], off
	s_waitcnt vmcnt(2) lgkmcnt(0)
	v_mov_b32_e32 v192, v189
	v_mov_b32_e32 v193, v190
	v_mov_b32_e32 v189, v191
	v_pk_add_f32 v[188:189], v[192:193], v[188:189]
	s_nop 0
	v_add_f32_e32 v112, v188, v189
	v_fmamk_f32 v112, v112, 0x3a800000, v231
	v_rsq_f32_e32 v112, v112
	s_nop 0
	v_pk_mul_f32 v[192:193], v[92:93], v[112:113] op_sel_hi:[1,0]
	v_pk_mul_f32 v[194:195], v[94:95], v[112:113] op_sel_hi:[1,0]
	v_pk_mul_f32 v[190:191], v[192:193], v[192:193]
	v_pk_mul_f32 v[188:189], v[194:195], v[194:195]
	v_pk_mul_f32 v[198:199], v[90:91], v[112:113] op_sel_hi:[1,0]
	v_pk_mov_b32 v[196:197], v[190:191], v[188:189] op_sel:[1,0]
	v_mov_b32_e32 v191, v189
	v_pk_add_f32 v[188:189], v[196:197], v[190:191]
	v_pk_mul_f32 v[196:197], v[88:89], v[112:113] op_sel_hi:[1,0]
	v_pk_mul_f32 v[190:191], v[198:199], v[198:199]
	v_pk_mul_f32 v[200:201], v[196:197], v[196:197]
	v_pk_mul_f32 v[224:225], v[84:85], v[112:113] op_sel_hi:[1,0]
	v_pk_mov_b32 v[202:203], v[200:201], v[190:191] op_sel:[1,0]
	v_mov_b32_e32 v201, v191
	v_pk_mul_f32 v[226:227], v[86:87], v[112:113] op_sel_hi:[1,0]
	v_pk_add_f32 v[190:191], v[202:203], v[200:201]
	v_pk_mul_f32 v[200:201], v[226:227], v[226:227]
	v_pk_mul_f32 v[202:203], v[224:225], v[224:225]
	v_add_f32_e32 v213, v200, v201
	v_add_f32_e32 v211, v202, v203
	v_pk_mul_f32 v[200:201], v[80:81], v[112:113] op_sel_hi:[1,0]
	v_pk_mul_f32 v[202:203], v[82:83], v[112:113] op_sel_hi:[1,0]
	v_pk_add_f32 v[188:189], v[188:189], v[188:189] op_sel_hi:[0,1]
	v_pk_add_f32 v[190:191], v[190:191], v[190:191] op_sel_hi:[0,1]
	v_pk_mul_f32 v[228:229], v[202:203], v[202:203]
	v_pk_mul_f32 v[232:233], v[200:201], v[200:201]
	v_mov_b32_e32 v188, v228
	v_mov_b32_e32 v210, v232
	v_mov_b32_e32 v212, v233
	v_mov_b32_e32 v190, v229
	v_pk_add_f32 v[210:211], v[210:211], v[212:213]
	v_pk_add_f32 v[188:189], v[188:189], v[190:191]
	s_nop 0
	v_pk_add_f32 v[188:189], v[210:211], v[188:189]
	s_nop 0
	v_add_f32_e32 v112, v188, v189
	ds_bpermute_b32 v188, v209, v112
	s_waitcnt lgkmcnt(0)
	v_add_f32_e32 v112, v112, v188
	ds_bpermute_b32 v188, v222, v112
	s_waitcnt lgkmcnt(0)
	v_add_f32_e32 v112, v112, v188
	v_lshlrev_b64 v[188:189], 7, v[186:187]
	v_lshl_add_u64 v[228:229], v[170:171], 0, v[188:189]
	v_lshl_add_u64 v[232:233], v[172:173], 0, v[188:189]
	s_waitcnt vmcnt(0)
	v_mov_b64_e32 v[188:189], v[246:247]
	v_mov_b64_e32 v[190:191], v[248:249]
	v_mov_b64_e32 v[210:211], v[250:251]
	v_mov_b64_e32 v[212:213], v[252:253]
	v_fmamk_f32 v112, v112, 0x3c800000, v231
	v_rsq_f32_e32 v112, v112
	s_nop 0
	v_pk_mul_f32 v[192:193], v[192:193], v[112:113] op_sel_hi:[1,0]
	v_pk_mul_f32 v[194:195], v[194:195], v[112:113] op_sel_hi:[1,0]
	v_pk_mul_f32 v[242:243], v[144:145], v[192:193]
	v_pk_mul_f32 v[192:193], v[224:225], v[112:113] op_sel_hi:[1,0]
	v_pk_mul_f32 v[244:245], v[146:147], v[194:195]
	v_pk_mul_f32 v[194:195], v[226:227], v[112:113] op_sel_hi:[1,0]
	v_pk_mul_f32 v[226:227], v[140:141], v[192:193]
	v_pk_mul_f32 v[224:225], v[142:143], v[194:195]
	v_pk_mul_f32 v[198:199], v[198:199], v[112:113] op_sel_hi:[1,0]
	v_pk_mul_f32 v[196:197], v[196:197], v[112:113] op_sel_hi:[1,0]
	s_waitcnt vmcnt(0) lgkmcnt(0)
	v_pk_mul_f32 v[194:195], v[210:211], v[226:227]
	v_pk_mul_f32 v[192:193], v[212:213], v[224:225]
	v_pk_fma_f32 v[194:195], v[188:189], v[242:243], v[194:195] neg_lo:[0,0,1] neg_hi:[0,0,1]
	v_pk_mul_f32 v[226:227], v[188:189], v[226:227]
	v_pk_mul_f32 v[188:189], v[190:191], v[224:225]
	v_pk_fma_f32 v[192:193], v[190:191], v[244:245], v[192:193] neg_lo:[0,0,1] neg_hi:[0,0,1]
	v_pk_fma_f32 v[188:189], v[212:213], v[244:245], v[188:189]
	v_pk_fma_f32 v[190:191], v[210:211], v[242:243], v[226:227]
	flat_load_dwordx4 v[210:213], v[228:229] offset:16
	flat_load_dwordx4 v[224:227], v[232:233] offset:16
	v_pk_mul_f32 v[228:229], v[136:137], v[196:197]
	v_pk_mul_f32 v[196:197], v[138:139], v[198:199]
	v_pk_mul_f32 v[198:199], v[200:201], v[112:113] op_sel_hi:[1,0]
	v_pk_mul_f32 v[200:201], v[202:203], v[112:113] op_sel_hi:[1,0]
	v_pk_mul_f32 v[198:199], v[132:133], v[198:199]
	v_pk_mul_f32 v[232:233], v[134:135], v[200:201]
	s_waitcnt vmcnt(0) lgkmcnt(0)
	v_pk_mul_f32 v[202:203], v[224:225], v[198:199]
	v_pk_mul_f32 v[200:201], v[226:227], v[232:233]
	v_pk_fma_f32 v[202:203], v[210:211], v[228:229], v[202:203] neg_lo:[0,0,1] neg_hi:[0,0,1]
	v_pk_mul_f32 v[198:199], v[210:211], v[198:199]
	v_pk_mul_f32 v[210:211], v[212:213], v[232:233]
	v_pk_fma_f32 v[200:201], v[212:213], v[196:197], v[200:201] neg_lo:[0,0,1] neg_hi:[0,0,1]
	v_pk_fma_f32 v[196:197], v[226:227], v[196:197], v[210:211]
	v_pk_fma_f32 v[198:199], v[224:225], v[228:229], v[198:199]
	s_cbranch_vccnz .LBB0_423
	v_pk_add_f32 v[162:163], v[162:163], v[192:193]
	v_pk_add_f32 v[160:161], v[160:161], v[194:195]
	v_pk_add_f32 v[158:159], v[158:159], v[200:201]
	v_pk_add_f32 v[156:157], v[156:157], v[202:203]
	v_pk_add_f32 v[154:155], v[154:155], v[188:189]
	v_pk_add_f32 v[152:153], v[152:153], v[190:191]
	v_pk_add_f32 v[150:151], v[150:151], v[196:197]
	v_pk_add_f32 v[148:149], v[148:149], v[198:199]
; __device__ __forceinline__ u32x4 pack8(const f32x4 a, const f32x4 b) { u32x4 w; w.x = cvt_pk_bf16(a[0], a[1]); w.y = cvt_pk_bf16(a[2], a[3]); w.z = cvt_pk_bf16(b[0], b[1]); w.w = cvt_pk_bf16(b[2], b[3]); return w; }
;     __device__ __forceinline__ void operator()(const f32x4 (&acc)[2][2][4][2], const Unit& u, int wr, int wc, int fr, int fq) const {
;     ...
;                 for (int m = 0; m < 4; ++m) { if (m == 0) asm volatile("" ::: "memory"); const int row = row0 + ai * HALF + m * 16; const float rs = rstd_of(ssq, row);
;                     f32x4 v[2][2]; float ss = 0.f;
; #pragma unroll
;                     for (int bj = 0; bj < 2; ++bj)
; #pragma unroll
;                         for (int n = 0; n < 2; ++n) { v[bj][n] = acc[ai][bj][m][n] * rs; const f32x4 q = v[bj][n] * v[bj][n]; ss += (q[0] + q[1]) + (q[2] + q[3]); }
;                     ss += __shfl_xor(ss, 16); ss += __shfl_xor(ss, 32);
;                     const float rn = __builtin_amdgcn_rsqf(ss * (1.0f / 64.0f) + 1e-6f);
;                     f32x4 o[2][2];
; #pragma unroll
;                     for (int n = 0; n < 2; ++n) { const f32x4 c = *(const f32x4*)(cosT + (size_t)row * 32 + 8 * fq + 4 * n), s = *(const f32x4*)(sinT + (size_t)row * 32 + 8 * fq + 4 * n);
;                         const f32x4 y1 = v[0][n] * rn * gv[0][n], y2 = v[1][n] * rn * gv[1][n];
;                         o[0][n] = y1 * c - y2 * s; o[1][n] = y2 * c + y1 * s; }
;                     if (dok) {
; #pragma unroll
;                         for (int bj = 0; bj < 2; ++bj)
; #pragma unroll
;                             for (int n = 0; n < 2; ++n) cs[bj][n] = cs[bj][n] + o[bj][n]; }
; #pragma unroll
;                     for (int bj = 0; bj < 2; ++bj) *(u32x4*)(ob + (size_t)row * 2816 + 32 * bj) = pack8(o[bj][0] * osc, o[bj][1] * osc); }
.LBB0_423:
	v_mad_i64_i32 v[210:211], s[12:13], v186, s92, v[180:181]
	v_pk_mul_f32 v[186:187], v[114:115], v[192:193]
	v_pk_mul_f32 v[192:193], v[184:185], v[194:195]
	v_pk_mul_f32 v[200:201], v[114:115], v[200:201]
	v_cvt_pk_bf16_f32 v192, v192, v193
	v_cvt_pk_bf16_f32 v193, v186, v187
	v_pk_mul_f32 v[188:189], v[114:115], v[188:189]
	v_pk_mul_f32 v[186:187], v[184:185], v[190:191]
	v_pk_mul_f32 v[114:115], v[114:115], v[196:197]
	v_pk_mul_f32 v[194:195], v[184:185], v[202:203]
	v_pk_mul_f32 v[190:191], v[184:185], v[198:199]
	v_cvt_pk_bf16_f32 v186, v186, v187
	v_cvt_pk_bf16_f32 v187, v188, v189
	v_cvt_pk_bf16_f32 v189, v114, v115
	v_or_b32_e32 v114, 48, v182
	v_cvt_pk_bf16_f32 v194, v194, v195
	v_cvt_pk_bf16_f32 v195, v200, v201
	v_cvt_pk_bf16_f32 v188, v190, v191
	v_ashrrev_i32_e32 v115, 31, v114
	flat_store_dwordx4 v[210:211], v[192:195]
	flat_store_dwordx4 v[210:211], v[186:189] offset:64
	s_and_b64 vcc, exec, s[10:11]
	s_nop 0
	v_lshl_add_u64 v[186:187], v[114:115], 4, s[18:19]
	flat_load_dwordx4 v[186:189], v[186:187]
	v_lshlrev_b64 v[250:251], 7, v[114:115]
	v_lshl_add_u64 v[246:247], v[170:171], 0, v[250:251]
	v_lshl_add_u64 v[250:251], v[172:173], 0, v[250:251]
	global_load_dwordx4 v[246:249], v[246:247], off
	global_load_dwordx4 v[250:253], v[250:251], off
	s_waitcnt vmcnt(2) lgkmcnt(0)
	v_mov_b32_e32 v190, v187
	v_mov_b32_e32 v191, v188
	v_mov_b32_e32 v187, v189
	v_pk_add_f32 v[186:187], v[190:191], v[186:187]
	s_nop 0
	v_add_f32_e32 v112, v186, v187
	v_fmamk_f32 v112, v112, 0x3a800000, v231
	v_rsq_f32_e32 v112, v112
	s_nop 0
	v_pk_mul_f32 v[190:191], v[76:77], v[112:113] op_sel_hi:[1,0]
	v_pk_mul_f32 v[192:193], v[78:79], v[112:113] op_sel_hi:[1,0]
	v_pk_mul_f32 v[188:189], v[190:191], v[190:191]
	v_pk_mul_f32 v[186:187], v[192:193], v[192:193]
	v_pk_mul_f32 v[196:197], v[74:75], v[112:113] op_sel_hi:[1,0]
	v_pk_mov_b32 v[194:195], v[188:189], v[186:187] op_sel:[1,0]
	v_mov_b32_e32 v189, v187
	v_pk_add_f32 v[186:187], v[194:195], v[188:189]
	v_pk_mul_f32 v[194:195], v[72:73], v[112:113] op_sel_hi:[1,0]
	v_pk_mul_f32 v[188:189], v[196:197], v[196:197]
	v_pk_mul_f32 v[198:199], v[194:195], v[194:195]
	v_pk_mul_f32 v[202:203], v[68:69], v[112:113] op_sel_hi:[1,0]
	v_pk_mov_b32 v[200:201], v[198:199], v[188:189] op_sel:[1,0]
	v_mov_b32_e32 v199, v189
	v_pk_mul_f32 v[224:225], v[70:71], v[112:113] op_sel_hi:[1,0]
	v_pk_add_f32 v[188:189], v[200:201], v[198:199]
	v_pk_mul_f32 v[198:199], v[224:225], v[224:225]
	v_pk_mul_f32 v[200:201], v[202:203], v[202:203]
	v_add_f32_e32 v213, v198, v199
	v_add_f32_e32 v211, v200, v201
	v_pk_mul_f32 v[198:199], v[64:65], v[112:113] op_sel_hi:[1,0]
	v_pk_mul_f32 v[200:201], v[66:67], v[112:113] op_sel_hi:[1,0]
	v_pk_add_f32 v[186:187], v[186:187], v[186:187] op_sel_hi:[0,1]
	v_pk_add_f32 v[188:189], v[188:189], v[188:189] op_sel_hi:[0,1]
	v_pk_mul_f32 v[226:227], v[200:201], v[200:201]
	v_pk_mul_f32 v[228:229], v[198:199], v[198:199]
	v_mov_b32_e32 v186, v226
	v_mov_b32_e32 v210, v228
	v_mov_b32_e32 v212, v229
	v_mov_b32_e32 v188, v227
	v_pk_add_f32 v[210:211], v[210:211], v[212:213]
	v_pk_add_f32 v[186:187], v[186:187], v[188:189]
	s_nop 0
	v_pk_add_f32 v[186:187], v[210:211], v[186:187]
	s_nop 0
	v_add_f32_e32 v112, v186, v187
	ds_bpermute_b32 v186, v209, v112
	s_waitcnt lgkmcnt(0)
	v_add_f32_e32 v112, v112, v186
	ds_bpermute_b32 v186, v222, v112
	s_waitcnt lgkmcnt(0)
	v_add_f32_e32 v112, v112, v186
	v_lshlrev_b64 v[186:187], 7, v[114:115]
	v_lshl_add_u64 v[226:227], v[170:171], 0, v[186:187]
	v_lshl_add_u64 v[228:229], v[172:173], 0, v[186:187]
	s_waitcnt vmcnt(0)
	v_mov_b64_e32 v[186:187], v[246:247]
	v_mov_b64_e32 v[188:189], v[248:249]
	v_mov_b64_e32 v[210:211], v[250:251]
	v_mov_b64_e32 v[212:213], v[252:253]
	v_fmamk_f32 v112, v112, 0x3c800000, v231
	v_rsq_f32_e32 v112, v112
	s_nop 0
	v_pk_mul_f32 v[190:191], v[190:191], v[112:113] op_sel_hi:[1,0]
	v_pk_mul_f32 v[192:193], v[192:193], v[112:113] op_sel_hi:[1,0]
	v_pk_mul_f32 v[232:233], v[144:145], v[190:191]
	v_pk_mul_f32 v[190:191], v[202:203], v[112:113] op_sel_hi:[1,0]
	v_pk_mul_f32 v[242:243], v[146:147], v[192:193]
	v_pk_mul_f32 v[192:193], v[224:225], v[112:113] op_sel_hi:[1,0]
	v_pk_mul_f32 v[224:225], v[140:141], v[190:191]
	v_pk_mul_f32 v[202:203], v[142:143], v[192:193]
	v_pk_mul_f32 v[196:197], v[196:197], v[112:113] op_sel_hi:[1,0]
	v_pk_mul_f32 v[194:195], v[194:195], v[112:113] op_sel_hi:[1,0]
	s_waitcnt vmcnt(0) lgkmcnt(0)
	v_pk_mul_f32 v[192:193], v[210:211], v[224:225]
	v_pk_mul_f32 v[190:191], v[212:213], v[202:203]
	v_pk_fma_f32 v[192:193], v[186:187], v[232:233], v[192:193] neg_lo:[0,0,1] neg_hi:[0,0,1]
	v_pk_mul_f32 v[224:225], v[186:187], v[224:225]
	v_pk_mul_f32 v[186:187], v[188:189], v[202:203]
	v_pk_fma_f32 v[190:191], v[188:189], v[242:243], v[190:191] neg_lo:[0,0,1] neg_hi:[0,0,1]
	v_pk_fma_f32 v[186:187], v[212:213], v[242:243], v[186:187]
	v_pk_fma_f32 v[188:189], v[210:211], v[232:233], v[224:225]
	flat_load_dwordx4 v[210:213], v[226:227] offset:16
	s_nop 0
	flat_load_dwordx4 v[224:227], v[228:229] offset:16
	v_pk_mul_f32 v[202:203], v[136:137], v[194:195]
	v_pk_mul_f32 v[194:195], v[138:139], v[196:197]
	v_pk_mul_f32 v[196:197], v[198:199], v[112:113] op_sel_hi:[1,0]
	v_pk_mul_f32 v[198:199], v[200:201], v[112:113] op_sel_hi:[1,0]
	v_pk_mul_f32 v[196:197], v[132:133], v[196:197]
	v_pk_mul_f32 v[228:229], v[134:135], v[198:199]
	s_waitcnt vmcnt(0) lgkmcnt(0)
	v_pk_mul_f32 v[200:201], v[224:225], v[196:197]
	v_pk_mul_f32 v[198:199], v[226:227], v[228:229]
	v_pk_fma_f32 v[200:201], v[210:211], v[202:203], v[200:201] neg_lo:[0,0,1] neg_hi:[0,0,1]
	v_pk_mul_f32 v[196:197], v[210:211], v[196:197]
	v_pk_mul_f32 v[210:211], v[212:213], v[228:229]
	v_pk_fma_f32 v[198:199], v[212:213], v[194:195], v[198:199] neg_lo:[0,0,1] neg_hi:[0,0,1]
	v_pk_fma_f32 v[194:195], v[226:227], v[194:195], v[210:211]
	v_pk_fma_f32 v[196:197], v[224:225], v[202:203], v[196:197]
	s_cbranch_vccnz .LBB0_425
	v_pk_add_f32 v[162:163], v[162:163], v[190:191]
	v_pk_add_f32 v[160:161], v[160:161], v[192:193]
	v_pk_add_f32 v[158:159], v[158:159], v[198:199]
	v_pk_add_f32 v[156:157], v[156:157], v[200:201]
	v_pk_add_f32 v[154:155], v[154:155], v[186:187]
	v_pk_add_f32 v[152:153], v[152:153], v[188:189]
	v_pk_add_f32 v[150:151], v[150:151], v[194:195]
	v_pk_add_f32 v[148:149], v[148:149], v[196:197]
; __device__ __forceinline__ u32x4 pack8(const f32x4 a, const f32x4 b) { u32x4 w; w.x = cvt_pk_bf16(a[0], a[1]); w.y = cvt_pk_bf16(a[2], a[3]); w.z = cvt_pk_bf16(b[0], b[1]); w.w = cvt_pk_bf16(b[2], b[3]); return w; }
;     __device__ __forceinline__ void operator()(const f32x4 (&acc)[2][2][4][2], const Unit& u, int wr, int wc, int fr, int fq) const {
;     ...
;                 for (int m = 0; m < 4; ++m) { if (m == 0) asm volatile("" ::: "memory"); const int row = row0 + ai * HALF + m * 16; const float rs = rstd_of(ssq, row);
;                     f32x4 v[2][2]; float ss = 0.f;
; #pragma unroll
;                     for (int bj = 0; bj < 2; ++bj)
; #pragma unroll
;                         for (int n = 0; n < 2; ++n) { v[bj][n] = acc[ai][bj][m][n] * rs; const f32x4 q = v[bj][n] * v[bj][n]; ss += (q[0] + q[1]) + (q[2] + q[3]); }
;                     ss += __shfl_xor(ss, 16); ss += __shfl_xor(ss, 32);
;                     const float rn = __builtin_amdgcn_rsqf(ss * (1.0f / 64.0f) + 1e-6f);
;                     f32x4 o[2][2];
; #pragma unroll
;                     for (int n = 0; n < 2; ++n) { const f32x4 c = *(const f32x4*)(cosT + (size_t)row * 32 + 8 * fq + 4 * n), s = *(const f32x4*)(sinT + (size_t)row * 32 + 8 * fq + 4 * n);
;                         const f32x4 y1 = v[0][n] * rn * gv[0][n], y2 = v[1][n] * rn * gv[1][n];
;                         o[0][n] = y1 * c - y2 * s; o[1][n] = y2 * c + y1 * s; }
;                     if (dok) {
; #pragma unroll
;                         for (int bj = 0; bj < 2; ++bj)
; #pragma unroll
;                             for (int n = 0; n < 2; ++n) cs[bj][n] = cs[bj][n] + o[bj][n]; }
; #pragma unroll
;                     for (int bj = 0; bj < 2; ++bj) *(u32x4*)(ob + (size_t)row * 2816 + 32 * bj) = pack8(o[bj][0] * osc, o[bj][1] * osc); }
.LBB0_425:
	v_mad_i64_i32 v[202:203], s[12:13], v114, s92, v[180:181]
	v_mov_b32_e32 v114, v184
	v_mov_b32_e32 v115, v184
	v_pk_mul_f32 v[210:211], v[114:115], v[190:191]
	v_pk_mul_f32 v[190:191], v[184:185], v[192:193]
	v_pk_mul_f32 v[198:199], v[114:115], v[198:199]
	v_pk_mul_f32 v[192:193], v[184:185], v[200:201]
	v_cvt_pk_bf16_f32 v190, v190, v191
	v_cvt_pk_bf16_f32 v191, v210, v211
	v_cvt_pk_bf16_f32 v192, v192, v193
	v_cvt_pk_bf16_f32 v193, v198, v199
	flat_store_dwordx4 v[202:203], v[190:193]
	s_and_b64 vcc, exec, s[10:11]
	s_nop 0
	v_pk_mul_f32 v[190:191], v[114:115], v[186:187]
	v_pk_mul_f32 v[186:187], v[184:185], v[188:189]
	v_pk_mul_f32 v[192:193], v[114:115], v[194:195]
	v_pk_mul_f32 v[188:189], v[184:185], v[196:197]
	v_cvt_pk_bf16_f32 v186, v186, v187
	v_cvt_pk_bf16_f32 v187, v190, v191
	v_cvt_pk_bf16_f32 v188, v188, v189
	v_cvt_pk_bf16_f32 v189, v192, v193
	flat_store_dwordx4 v[202:203], v[186:189] offset:64
	s_nop 1
	v_add_u32_e32 v186, 0x80, v182
	v_ashrrev_i32_e32 v187, 31, v186
	v_lshl_add_u64 v[188:189], v[186:187], 4, s[18:19]
	flat_load_dwordx4 v[188:191], v[188:189]
	v_lshlrev_b64 v[250:251], 7, v[186:187]
	v_lshl_add_u64 v[246:247], v[170:171], 0, v[250:251]
	v_lshl_add_u64 v[250:251], v[172:173], 0, v[250:251]
	global_load_dwordx4 v[246:249], v[246:247], off
	global_load_dwordx4 v[250:253], v[250:251], off
	s_waitcnt vmcnt(2) lgkmcnt(0)
	v_mov_b32_e32 v192, v189
	v_mov_b32_e32 v193, v190
	v_mov_b32_e32 v189, v191
	v_pk_add_f32 v[188:189], v[192:193], v[188:189]
	s_nop 0
	v_add_f32_e32 v112, v188, v189
	v_fmamk_f32 v112, v112, 0x3a800000, v231
	v_rsq_f32_e32 v112, v112
	s_nop 0
	v_pk_mul_f32 v[192:193], v[60:61], v[112:113] op_sel_hi:[1,0]
	v_pk_mul_f32 v[194:195], v[62:63], v[112:113] op_sel_hi:[1,0]
	v_pk_mul_f32 v[190:191], v[192:193], v[192:193]
	v_pk_mul_f32 v[188:189], v[194:195], v[194:195]
	v_pk_mul_f32 v[198:199], v[58:59], v[112:113] op_sel_hi:[1,0]
	v_pk_mov_b32 v[196:197], v[190:191], v[188:189] op_sel:[1,0]
	v_mov_b32_e32 v191, v189
	v_pk_add_f32 v[188:189], v[196:197], v[190:191]
	v_pk_mul_f32 v[196:197], v[56:57], v[112:113] op_sel_hi:[1,0]
	v_pk_mul_f32 v[190:191], v[198:199], v[198:199]
	v_pk_mul_f32 v[200:201], v[196:197], v[196:197]
	v_pk_mul_f32 v[224:225], v[52:53], v[112:113] op_sel_hi:[1,0]
	v_pk_mov_b32 v[202:203], v[200:201], v[190:191] op_sel:[1,0]
	v_mov_b32_e32 v201, v191
	v_pk_mul_f32 v[226:227], v[54:55], v[112:113] op_sel_hi:[1,0]
	v_pk_add_f32 v[190:191], v[202:203], v[200:201]
	v_pk_mul_f32 v[200:201], v[226:227], v[226:227]
	v_pk_mul_f32 v[202:203], v[224:225], v[224:225]
	v_add_f32_e32 v213, v200, v201
	v_add_f32_e32 v211, v202, v203
	v_pk_mul_f32 v[200:201], v[48:49], v[112:113] op_sel_hi:[1,0]
	v_pk_mul_f32 v[202:203], v[50:51], v[112:113] op_sel_hi:[1,0]
	v_pk_add_f32 v[188:189], v[188:189], v[188:189] op_sel_hi:[0,1]
	v_pk_add_f32 v[190:191], v[190:191], v[190:191] op_sel_hi:[0,1]
	v_pk_mul_f32 v[228:229], v[202:203], v[202:203]
	v_pk_mul_f32 v[232:233], v[200:201], v[200:201]
	v_mov_b32_e32 v188, v228
	v_mov_b32_e32 v210, v232
	v_mov_b32_e32 v212, v233
	v_mov_b32_e32 v190, v229
	v_pk_add_f32 v[210:211], v[210:211], v[212:213]
	v_pk_add_f32 v[188:189], v[188:189], v[190:191]
	s_nop 0
	v_pk_add_f32 v[188:189], v[210:211], v[188:189]
	s_nop 0
	v_add_f32_e32 v112, v188, v189
	ds_bpermute_b32 v188, v209, v112
	s_waitcnt lgkmcnt(0)
	v_add_f32_e32 v112, v112, v188
	ds_bpermute_b32 v188, v222, v112
	s_waitcnt lgkmcnt(0)
	v_add_f32_e32 v112, v112, v188
	v_lshlrev_b64 v[188:189], 7, v[186:187]
	v_lshl_add_u64 v[228:229], v[170:171], 0, v[188:189]
	v_lshl_add_u64 v[232:233], v[172:173], 0, v[188:189]
	s_waitcnt vmcnt(0)
	v_mov_b64_e32 v[188:189], v[246:247]
	v_mov_b64_e32 v[190:191], v[248:249]
	v_mov_b64_e32 v[210:211], v[250:251]
	v_mov_b64_e32 v[212:213], v[252:253]
	v_fmamk_f32 v112, v112, 0x3c800000, v231
	v_rsq_f32_e32 v112, v112
	s_nop 0
	v_pk_mul_f32 v[192:193], v[192:193], v[112:113] op_sel_hi:[1,0]
	v_pk_mul_f32 v[194:195], v[194:195], v[112:113] op_sel_hi:[1,0]
	v_pk_mul_f32 v[242:243], v[144:145], v[192:193]
	v_pk_mul_f32 v[192:193], v[224:225], v[112:113] op_sel_hi:[1,0]
	v_pk_mul_f32 v[244:245], v[146:147], v[194:195]
	v_pk_mul_f32 v[194:195], v[226:227], v[112:113] op_sel_hi:[1,0]
	v_pk_mul_f32 v[226:227], v[140:141], v[192:193]
	v_pk_mul_f32 v[224:225], v[142:143], v[194:195]
	v_pk_mul_f32 v[198:199], v[198:199], v[112:113] op_sel_hi:[1,0]
	v_pk_mul_f32 v[196:197], v[196:197], v[112:113] op_sel_hi:[1,0]
	s_waitcnt vmcnt(0) lgkmcnt(0)
	v_pk_mul_f32 v[194:195], v[210:211], v[226:227]
	v_pk_mul_f32 v[192:193], v[212:213], v[224:225]
	v_pk_fma_f32 v[194:195], v[188:189], v[242:243], v[194:195] neg_lo:[0,0,1] neg_hi:[0,0,1]
	v_pk_mul_f32 v[226:227], v[188:189], v[226:227]
	v_pk_mul_f32 v[188:189], v[190:191], v[224:225]
	v_pk_fma_f32 v[192:193], v[190:191], v[244:245], v[192:193] neg_lo:[0,0,1] neg_hi:[0,0,1]
	v_pk_fma_f32 v[188:189], v[212:213], v[244:245], v[188:189]
	v_pk_fma_f32 v[190:191], v[210:211], v[242:243], v[226:227]
	flat_load_dwordx4 v[210:213], v[228:229] offset:16
	flat_load_dwordx4 v[224:227], v[232:233] offset:16
	v_pk_mul_f32 v[228:229], v[136:137], v[196:197]
	v_pk_mul_f32 v[196:197], v[138:139], v[198:199]
	v_pk_mul_f32 v[198:199], v[200:201], v[112:113] op_sel_hi:[1,0]
	v_pk_mul_f32 v[200:201], v[202:203], v[112:113] op_sel_hi:[1,0]
	v_pk_mul_f32 v[198:199], v[132:133], v[198:199]
	v_pk_mul_f32 v[232:233], v[134:135], v[200:201]
	s_waitcnt vmcnt(0) lgkmcnt(0)
	v_pk_mul_f32 v[202:203], v[224:225], v[198:199]
	v_pk_mul_f32 v[200:201], v[226:227], v[232:233]
	v_pk_fma_f32 v[202:203], v[210:211], v[228:229], v[202:203] neg_lo:[0,0,1] neg_hi:[0,0,1]
	v_pk_mul_f32 v[198:199], v[210:211], v[198:199]
	v_pk_mul_f32 v[210:211], v[212:213], v[232:233]
	v_pk_fma_f32 v[200:201], v[212:213], v[196:197], v[200:201] neg_lo:[0,0,1] neg_hi:[0,0,1]
	v_pk_fma_f32 v[196:197], v[226:227], v[196:197], v[210:211]
	v_pk_fma_f32 v[198:199], v[224:225], v[228:229], v[198:199]
	s_cbranch_vccnz .LBB0_427
	v_pk_add_f32 v[162:163], v[162:163], v[192:193]
	v_pk_add_f32 v[160:161], v[160:161], v[194:195]
	v_pk_add_f32 v[158:159], v[158:159], v[200:201]
	v_pk_add_f32 v[156:157], v[156:157], v[202:203]
	v_pk_add_f32 v[154:155], v[154:155], v[188:189]
	v_pk_add_f32 v[152:153], v[152:153], v[190:191]
	v_pk_add_f32 v[150:151], v[150:151], v[196:197]
	v_pk_add_f32 v[148:149], v[148:149], v[198:199]
; __device__ __forceinline__ u32x4 pack8(const f32x4 a, const f32x4 b) { u32x4 w; w.x = cvt_pk_bf16(a[0], a[1]); w.y = cvt_pk_bf16(a[2], a[3]); w.z = cvt_pk_bf16(b[0], b[1]); w.w = cvt_pk_bf16(b[2], b[3]); return w; }
;     __device__ __forceinline__ void operator()(const f32x4 (&acc)[2][2][4][2], const Unit& u, int wr, int wc, int fr, int fq) const {
;     ...
;                 for (int m = 0; m < 4; ++m) { if (m == 0) asm volatile("" ::: "memory"); const int row = row0 + ai * HALF + m * 16; const float rs = rstd_of(ssq, row);
;                     f32x4 v[2][2]; float ss = 0.f;
; #pragma unroll
;                     for (int bj = 0; bj < 2; ++bj)
; #pragma unroll
;                         for (int n = 0; n < 2; ++n) { v[bj][n] = acc[ai][bj][m][n] * rs; const f32x4 q = v[bj][n] * v[bj][n]; ss += (q[0] + q[1]) + (q[2] + q[3]); }
;                     ss += __shfl_xor(ss, 16); ss += __shfl_xor(ss, 32);
;                     const float rn = __builtin_amdgcn_rsqf(ss * (1.0f / 64.0f) + 1e-6f);
;                     f32x4 o[2][2];
; #pragma unroll
;                     for (int n = 0; n < 2; ++n) { const f32x4 c = *(const f32x4*)(cosT + (size_t)row * 32 + 8 * fq + 4 * n), s = *(const f32x4*)(sinT + (size_t)row * 32 + 8 * fq + 4 * n);
;                         const f32x4 y1 = v[0][n] * rn * gv[0][n], y2 = v[1][n] * rn * gv[1][n];
;                         o[0][n] = y1 * c - y2 * s; o[1][n] = y2 * c + y1 * s; }
;                     if (dok) {
; #pragma unroll
;                         for (int bj = 0; bj < 2; ++bj)
; #pragma unroll
;                             for (int n = 0; n < 2; ++n) cs[bj][n] = cs[bj][n] + o[bj][n]; }
; #pragma unroll
;                     for (int bj = 0; bj < 2; ++bj) *(u32x4*)(ob + (size_t)row * 2816 + 32 * bj) = pack8(o[bj][0] * osc, o[bj][1] * osc); }
.LBB0_427:
	v_mad_i64_i32 v[210:211], s[12:13], v186, s92, v[180:181]
	v_pk_mul_f32 v[186:187], v[114:115], v[192:193]
	v_pk_mul_f32 v[192:193], v[184:185], v[194:195]
	v_pk_mul_f32 v[200:201], v[114:115], v[200:201]
	v_cvt_pk_bf16_f32 v192, v192, v193
	v_cvt_pk_bf16_f32 v193, v186, v187
	v_pk_mul_f32 v[188:189], v[114:115], v[188:189]
	v_pk_mul_f32 v[186:187], v[184:185], v[190:191]
	v_pk_mul_f32 v[114:115], v[114:115], v[196:197]
	v_pk_mul_f32 v[194:195], v[184:185], v[202:203]
	v_pk_mul_f32 v[190:191], v[184:185], v[198:199]
	v_cvt_pk_bf16_f32 v186, v186, v187
	v_cvt_pk_bf16_f32 v187, v188, v189
	v_cvt_pk_bf16_f32 v189, v114, v115
	v_add_u32_e32 v114, 0x90, v182
	v_cvt_pk_bf16_f32 v194, v194, v195
	v_cvt_pk_bf16_f32 v195, v200, v201
	v_cvt_pk_bf16_f32 v188, v190, v191
	v_ashrrev_i32_e32 v115, 31, v114
	flat_store_dwordx4 v[210:211], v[192:195]
	flat_store_dwordx4 v[210:211], v[186:189] offset:64
	s_and_b64 vcc, exec, s[10:11]
	s_nop 0
	v_lshl_add_u64 v[186:187], v[114:115], 4, s[18:19]
	flat_load_dwordx4 v[186:189], v[186:187]
	v_lshlrev_b64 v[250:251], 7, v[114:115]
	v_lshl_add_u64 v[246:247], v[170:171], 0, v[250:251]
	v_lshl_add_u64 v[250:251], v[172:173], 0, v[250:251]
	global_load_dwordx4 v[246:249], v[246:247], off
	global_load_dwordx4 v[250:253], v[250:251], off
	s_waitcnt vmcnt(2) lgkmcnt(0)
	v_mov_b32_e32 v190, v187
	v_mov_b32_e32 v191, v188
	v_mov_b32_e32 v187, v189
	v_pk_add_f32 v[186:187], v[190:191], v[186:187]
	s_nop 0
	v_add_f32_e32 v112, v186, v187
	v_fmamk_f32 v112, v112, 0x3a800000, v231
	v_rsq_f32_e32 v112, v112
	s_nop 0
	v_pk_mul_f32 v[190:191], v[44:45], v[112:113] op_sel_hi:[1,0]
	v_pk_mul_f32 v[192:193], v[46:47], v[112:113] op_sel_hi:[1,0]
	v_pk_mul_f32 v[188:189], v[190:191], v[190:191]
	v_pk_mul_f32 v[186:187], v[192:193], v[192:193]
	v_pk_mul_f32 v[196:197], v[42:43], v[112:113] op_sel_hi:[1,0]
	v_pk_mov_b32 v[194:195], v[188:189], v[186:187] op_sel:[1,0]
	v_mov_b32_e32 v189, v187
	v_pk_add_f32 v[186:187], v[194:195], v[188:189]
	v_pk_mul_f32 v[194:195], v[40:41], v[112:113] op_sel_hi:[1,0]
	v_pk_mul_f32 v[188:189], v[196:197], v[196:197]
	v_pk_mul_f32 v[198:199], v[194:195], v[194:195]
	v_pk_mul_f32 v[202:203], v[36:37], v[112:113] op_sel_hi:[1,0]
	v_pk_mov_b32 v[200:201], v[198:199], v[188:189] op_sel:[1,0]
	v_mov_b32_e32 v199, v189
	v_pk_mul_f32 v[224:225], v[38:39], v[112:113] op_sel_hi:[1,0]
	v_pk_add_f32 v[188:189], v[200:201], v[198:199]
	v_pk_mul_f32 v[198:199], v[224:225], v[224:225]
	v_pk_mul_f32 v[200:201], v[202:203], v[202:203]
	v_add_f32_e32 v213, v198, v199
	v_add_f32_e32 v211, v200, v201
	v_pk_mul_f32 v[198:199], v[32:33], v[112:113] op_sel_hi:[1,0]
	v_pk_mul_f32 v[200:201], v[34:35], v[112:113] op_sel_hi:[1,0]
	v_pk_add_f32 v[186:187], v[186:187], v[186:187] op_sel_hi:[0,1]
	v_pk_add_f32 v[188:189], v[188:189], v[188:189] op_sel_hi:[0,1]
	v_pk_mul_f32 v[226:227], v[200:201], v[200:201]
	v_pk_mul_f32 v[228:229], v[198:199], v[198:199]
	v_mov_b32_e32 v186, v226
	v_mov_b32_e32 v210, v228
	v_mov_b32_e32 v212, v229
	v_mov_b32_e32 v188, v227
	v_pk_add_f32 v[210:211], v[210:211], v[212:213]
	v_pk_add_f32 v[186:187], v[186:187], v[188:189]
	s_nop 0
	v_pk_add_f32 v[186:187], v[210:211], v[186:187]
	s_nop 0
	v_add_f32_e32 v112, v186, v187
	ds_bpermute_b32 v186, v209, v112
	s_waitcnt lgkmcnt(0)
	v_add_f32_e32 v112, v112, v186
	ds_bpermute_b32 v186, v222, v112
	s_waitcnt lgkmcnt(0)
	v_add_f32_e32 v112, v112, v186
	v_lshlrev_b64 v[186:187], 7, v[114:115]
	v_lshl_add_u64 v[226:227], v[170:171], 0, v[186:187]
	v_lshl_add_u64 v[228:229], v[172:173], 0, v[186:187]
	s_waitcnt vmcnt(0)
	v_mov_b64_e32 v[186:187], v[246:247]
	v_mov_b64_e32 v[188:189], v[248:249]
	v_mov_b64_e32 v[210:211], v[250:251]
	v_mov_b64_e32 v[212:213], v[252:253]
	v_fmamk_f32 v112, v112, 0x3c800000, v231
	v_rsq_f32_e32 v112, v112
	s_nop 0
	v_pk_mul_f32 v[190:191], v[190:191], v[112:113] op_sel_hi:[1,0]
	v_pk_mul_f32 v[192:193], v[192:193], v[112:113] op_sel_hi:[1,0]
	v_pk_mul_f32 v[232:233], v[144:145], v[190:191]
	v_pk_mul_f32 v[190:191], v[202:203], v[112:113] op_sel_hi:[1,0]
	v_pk_mul_f32 v[242:243], v[146:147], v[192:193]
	v_pk_mul_f32 v[192:193], v[224:225], v[112:113] op_sel_hi:[1,0]
	v_pk_mul_f32 v[224:225], v[140:141], v[190:191]
	v_pk_mul_f32 v[202:203], v[142:143], v[192:193]
	v_pk_mul_f32 v[196:197], v[196:197], v[112:113] op_sel_hi:[1,0]
	v_pk_mul_f32 v[194:195], v[194:195], v[112:113] op_sel_hi:[1,0]
	s_waitcnt vmcnt(0) lgkmcnt(0)
	v_pk_mul_f32 v[192:193], v[210:211], v[224:225]
	v_pk_mul_f32 v[190:191], v[212:213], v[202:203]
	v_pk_fma_f32 v[192:193], v[186:187], v[232:233], v[192:193] neg_lo:[0,0,1] neg_hi:[0,0,1]
	v_pk_mul_f32 v[224:225], v[186:187], v[224:225]
	v_pk_mul_f32 v[186:187], v[188:189], v[202:203]
	v_pk_fma_f32 v[190:191], v[188:189], v[242:243], v[190:191] neg_lo:[0,0,1] neg_hi:[0,0,1]
	v_pk_fma_f32 v[186:187], v[212:213], v[242:243], v[186:187]
	v_pk_fma_f32 v[188:189], v[210:211], v[232:233], v[224:225]
	flat_load_dwordx4 v[210:213], v[226:227] offset:16
	s_nop 0
	flat_load_dwordx4 v[224:227], v[228:229] offset:16
	v_pk_mul_f32 v[202:203], v[136:137], v[194:195]
	v_pk_mul_f32 v[194:195], v[138:139], v[196:197]
	v_pk_mul_f32 v[196:197], v[198:199], v[112:113] op_sel_hi:[1,0]
	v_pk_mul_f32 v[198:199], v[200:201], v[112:113] op_sel_hi:[1,0]
	v_pk_mul_f32 v[196:197], v[132:133], v[196:197]
	v_pk_mul_f32 v[228:229], v[134:135], v[198:199]
	s_waitcnt vmcnt(0) lgkmcnt(0)
	v_pk_mul_f32 v[200:201], v[224:225], v[196:197]
	v_pk_mul_f32 v[198:199], v[226:227], v[228:229]
	v_pk_fma_f32 v[200:201], v[210:211], v[202:203], v[200:201] neg_lo:[0,0,1] neg_hi:[0,0,1]
	v_pk_mul_f32 v[196:197], v[210:211], v[196:197]
	v_pk_mul_f32 v[210:211], v[212:213], v[228:229]
	v_pk_fma_f32 v[198:199], v[212:213], v[194:195], v[198:199] neg_lo:[0,0,1] neg_hi:[0,0,1]
	v_pk_fma_f32 v[194:195], v[226:227], v[194:195], v[210:211]
	v_pk_fma_f32 v[196:197], v[224:225], v[202:203], v[196:197]
	s_cbranch_vccnz .LBB0_429
	v_pk_add_f32 v[162:163], v[162:163], v[190:191]
	v_pk_add_f32 v[160:161], v[160:161], v[192:193]
	v_pk_add_f32 v[158:159], v[158:159], v[198:199]
	v_pk_add_f32 v[156:157], v[156:157], v[200:201]
	v_pk_add_f32 v[154:155], v[154:155], v[186:187]
	v_pk_add_f32 v[152:153], v[152:153], v[188:189]
	v_pk_add_f32 v[150:151], v[150:151], v[194:195]
	v_pk_add_f32 v[148:149], v[148:149], v[196:197]
; __device__ __forceinline__ u32x4 pack8(const f32x4 a, const f32x4 b) { u32x4 w; w.x = cvt_pk_bf16(a[0], a[1]); w.y = cvt_pk_bf16(a[2], a[3]); w.z = cvt_pk_bf16(b[0], b[1]); w.w = cvt_pk_bf16(b[2], b[3]); return w; }
;     __device__ __forceinline__ void operator()(const f32x4 (&acc)[2][2][4][2], const Unit& u, int wr, int wc, int fr, int fq) const {
;     ...
;                 for (int m = 0; m < 4; ++m) { if (m == 0) asm volatile("" ::: "memory"); const int row = row0 + ai * HALF + m * 16; const float rs = rstd_of(ssq, row);
;                     f32x4 v[2][2]; float ss = 0.f;
; #pragma unroll
;                     for (int bj = 0; bj < 2; ++bj)
; #pragma unroll
;                         for (int n = 0; n < 2; ++n) { v[bj][n] = acc[ai][bj][m][n] * rs; const f32x4 q = v[bj][n] * v[bj][n]; ss += (q[0] + q[1]) + (q[2] + q[3]); }
;                     ss += __shfl_xor(ss, 16); ss += __shfl_xor(ss, 32);
;                     const float rn = __builtin_amdgcn_rsqf(ss * (1.0f / 64.0f) + 1e-6f);
;                     f32x4 o[2][2];
; #pragma unroll
;                     for (int n = 0; n < 2; ++n) { const f32x4 c = *(const f32x4*)(cosT + (size_t)row * 32 + 8 * fq + 4 * n), s = *(const f32x4*)(sinT + (size_t)row * 32 + 8 * fq + 4 * n);
;                         const f32x4 y1 = v[0][n] * rn * gv[0][n], y2 = v[1][n] * rn * gv[1][n];
;                         o[0][n] = y1 * c - y2 * s; o[1][n] = y2 * c + y1 * s; }
;                     if (dok) {
; #pragma unroll
;                         for (int bj = 0; bj < 2; ++bj)
; #pragma unroll
;                             for (int n = 0; n < 2; ++n) cs[bj][n] = cs[bj][n] + o[bj][n]; }
; #pragma unroll
;                     for (int bj = 0; bj < 2; ++bj) *(u32x4*)(ob + (size_t)row * 2816 + 32 * bj) = pack8(o[bj][0] * osc, o[bj][1] * osc); }
.LBB0_429:
	v_mad_i64_i32 v[202:203], s[12:13], v114, s92, v[180:181]
	v_mov_b32_e32 v114, v184
	v_mov_b32_e32 v115, v184
	v_pk_mul_f32 v[210:211], v[114:115], v[190:191]
	v_pk_mul_f32 v[190:191], v[184:185], v[192:193]
	v_pk_mul_f32 v[198:199], v[114:115], v[198:199]
	v_pk_mul_f32 v[192:193], v[184:185], v[200:201]
	v_cvt_pk_bf16_f32 v190, v190, v191
	v_cvt_pk_bf16_f32 v191, v210, v211
	v_cvt_pk_bf16_f32 v192, v192, v193
	v_cvt_pk_bf16_f32 v193, v198, v199
	flat_store_dwordx4 v[202:203], v[190:193]
	s_and_b64 vcc, exec, s[10:11]
	s_nop 0
	v_pk_mul_f32 v[190:191], v[114:115], v[186:187]
	v_pk_mul_f32 v[186:187], v[184:185], v[188:189]
	v_pk_mul_f32 v[192:193], v[114:115], v[194:195]
	v_pk_mul_f32 v[188:189], v[184:185], v[196:197]
	v_cvt_pk_bf16_f32 v186, v186, v187
	v_cvt_pk_bf16_f32 v187, v190, v191
	v_cvt_pk_bf16_f32 v188, v188, v189
	v_cvt_pk_bf16_f32 v189, v192, v193
	flat_store_dwordx4 v[202:203], v[186:189] offset:64
	s_nop 1
	v_add_u32_e32 v186, 0xa0, v182
	v_ashrrev_i32_e32 v187, 31, v186
	v_lshl_add_u64 v[188:189], v[186:187], 4, s[18:19]
	flat_load_dwordx4 v[188:191], v[188:189]
	v_lshlrev_b64 v[250:251], 7, v[186:187]
	v_lshl_add_u64 v[246:247], v[170:171], 0, v[250:251]
	v_lshl_add_u64 v[250:251], v[172:173], 0, v[250:251]
	global_load_dwordx4 v[246:249], v[246:247], off
	global_load_dwordx4 v[250:253], v[250:251], off
	s_waitcnt vmcnt(2) lgkmcnt(0)
	v_mov_b32_e32 v192, v189
	v_mov_b32_e32 v193, v190
	v_mov_b32_e32 v189, v191
	v_pk_add_f32 v[188:189], v[192:193], v[188:189]
	s_nop 0
	v_add_f32_e32 v112, v188, v189
	v_fmamk_f32 v112, v112, 0x3a800000, v231
	v_rsq_f32_e32 v112, v112
	s_nop 0
	v_pk_mul_f32 v[192:193], v[28:29], v[112:113] op_sel_hi:[1,0]
	v_pk_mul_f32 v[194:195], v[30:31], v[112:113] op_sel_hi:[1,0]
	v_pk_mul_f32 v[190:191], v[192:193], v[192:193]
	v_pk_mul_f32 v[188:189], v[194:195], v[194:195]
	v_pk_mul_f32 v[198:199], v[26:27], v[112:113] op_sel_hi:[1,0]
	v_pk_mov_b32 v[196:197], v[190:191], v[188:189] op_sel:[1,0]
	v_mov_b32_e32 v191, v189
	v_pk_add_f32 v[188:189], v[196:197], v[190:191]
	v_pk_mul_f32 v[196:197], v[24:25], v[112:113] op_sel_hi:[1,0]
	v_pk_mul_f32 v[190:191], v[198:199], v[198:199]
	v_pk_mul_f32 v[200:201], v[196:197], v[196:197]
	v_pk_mul_f32 v[224:225], v[20:21], v[112:113] op_sel_hi:[1,0]
	v_pk_mov_b32 v[202:203], v[200:201], v[190:191] op_sel:[1,0]
	v_mov_b32_e32 v201, v191
	v_pk_mul_f32 v[226:227], v[22:23], v[112:113] op_sel_hi:[1,0]
	v_pk_add_f32 v[190:191], v[202:203], v[200:201]
	v_pk_mul_f32 v[200:201], v[226:227], v[226:227]
	v_pk_mul_f32 v[202:203], v[224:225], v[224:225]
	v_add_f32_e32 v213, v200, v201
	v_add_f32_e32 v211, v202, v203
	v_pk_mul_f32 v[200:201], v[16:17], v[112:113] op_sel_hi:[1,0]
	v_pk_mul_f32 v[202:203], v[18:19], v[112:113] op_sel_hi:[1,0]
	v_pk_add_f32 v[188:189], v[188:189], v[188:189] op_sel_hi:[0,1]
	v_pk_add_f32 v[190:191], v[190:191], v[190:191] op_sel_hi:[0,1]
	v_pk_mul_f32 v[228:229], v[202:203], v[202:203]
	v_pk_mul_f32 v[232:233], v[200:201], v[200:201]
	v_mov_b32_e32 v188, v228
	v_mov_b32_e32 v210, v232
	v_mov_b32_e32 v212, v233
	v_mov_b32_e32 v190, v229
	v_pk_add_f32 v[210:211], v[210:211], v[212:213]
	v_pk_add_f32 v[188:189], v[188:189], v[190:191]
	s_nop 0
	v_pk_add_f32 v[188:189], v[210:211], v[188:189]
	s_nop 0
	v_add_f32_e32 v112, v188, v189
	ds_bpermute_b32 v188, v209, v112
	s_waitcnt lgkmcnt(0)
	v_add_f32_e32 v112, v112, v188
	ds_bpermute_b32 v188, v222, v112
	s_waitcnt lgkmcnt(0)
	v_add_f32_e32 v112, v112, v188
	v_lshlrev_b64 v[188:189], 7, v[186:187]
	v_lshl_add_u64 v[228:229], v[170:171], 0, v[188:189]
	v_lshl_add_u64 v[232:233], v[172:173], 0, v[188:189]
	s_waitcnt vmcnt(0)
	v_mov_b64_e32 v[188:189], v[246:247]
	v_mov_b64_e32 v[190:191], v[248:249]
	v_mov_b64_e32 v[210:211], v[250:251]
	v_mov_b64_e32 v[212:213], v[252:253]
	v_fmamk_f32 v112, v112, 0x3c800000, v231
	v_rsq_f32_e32 v112, v112
	s_nop 0
	v_pk_mul_f32 v[192:193], v[192:193], v[112:113] op_sel_hi:[1,0]
	v_pk_mul_f32 v[194:195], v[194:195], v[112:113] op_sel_hi:[1,0]
	v_pk_mul_f32 v[242:243], v[144:145], v[192:193]
	v_pk_mul_f32 v[192:193], v[224:225], v[112:113] op_sel_hi:[1,0]
	v_pk_mul_f32 v[244:245], v[146:147], v[194:195]
	v_pk_mul_f32 v[194:195], v[226:227], v[112:113] op_sel_hi:[1,0]
	v_pk_mul_f32 v[226:227], v[140:141], v[192:193]
	v_pk_mul_f32 v[224:225], v[142:143], v[194:195]
	v_pk_mul_f32 v[198:199], v[198:199], v[112:113] op_sel_hi:[1,0]
	v_pk_mul_f32 v[196:197], v[196:197], v[112:113] op_sel_hi:[1,0]
	s_waitcnt vmcnt(0) lgkmcnt(0)
	v_pk_mul_f32 v[194:195], v[210:211], v[226:227]
	v_pk_mul_f32 v[192:193], v[212:213], v[224:225]
	v_pk_fma_f32 v[194:195], v[188:189], v[242:243], v[194:195] neg_lo:[0,0,1] neg_hi:[0,0,1]
	v_pk_mul_f32 v[226:227], v[188:189], v[226:227]
	v_pk_mul_f32 v[188:189], v[190:191], v[224:225]
	v_pk_fma_f32 v[192:193], v[190:191], v[244:245], v[192:193] neg_lo:[0,0,1] neg_hi:[0,0,1]
	v_pk_fma_f32 v[188:189], v[212:213], v[244:245], v[188:189]
	v_pk_fma_f32 v[190:191], v[210:211], v[242:243], v[226:227]
	flat_load_dwordx4 v[210:213], v[228:229] offset:16
	flat_load_dwordx4 v[224:227], v[232:233] offset:16
	v_pk_mul_f32 v[228:229], v[136:137], v[196:197]
	v_pk_mul_f32 v[196:197], v[138:139], v[198:199]
	v_pk_mul_f32 v[198:199], v[200:201], v[112:113] op_sel_hi:[1,0]
	v_pk_mul_f32 v[200:201], v[202:203], v[112:113] op_sel_hi:[1,0]
	v_pk_mul_f32 v[198:199], v[132:133], v[198:199]
	v_pk_mul_f32 v[232:233], v[134:135], v[200:201]
	s_waitcnt vmcnt(0) lgkmcnt(0)
	v_pk_mul_f32 v[202:203], v[224:225], v[198:199]
	v_pk_mul_f32 v[200:201], v[226:227], v[232:233]
	v_pk_fma_f32 v[202:203], v[210:211], v[228:229], v[202:203] neg_lo:[0,0,1] neg_hi:[0,0,1]
	v_pk_mul_f32 v[198:199], v[210:211], v[198:199]
	v_pk_mul_f32 v[210:211], v[212:213], v[232:233]
	v_pk_fma_f32 v[200:201], v[212:213], v[196:197], v[200:201] neg_lo:[0,0,1] neg_hi:[0,0,1]
	v_pk_fma_f32 v[196:197], v[226:227], v[196:197], v[210:211]
	v_pk_fma_f32 v[198:199], v[224:225], v[228:229], v[198:199]
	s_cbranch_vccnz .LBB0_431
	v_pk_add_f32 v[162:163], v[162:163], v[192:193]
	v_pk_add_f32 v[160:161], v[160:161], v[194:195]
	v_pk_add_f32 v[158:159], v[158:159], v[200:201]
	v_pk_add_f32 v[156:157], v[156:157], v[202:203]
	v_pk_add_f32 v[154:155], v[154:155], v[188:189]
	v_pk_add_f32 v[152:153], v[152:153], v[190:191]
	v_pk_add_f32 v[150:151], v[150:151], v[196:197]
	v_pk_add_f32 v[148:149], v[148:149], v[198:199]
; __device__ __forceinline__ u32x4 pack8(const f32x4 a, const f32x4 b) { u32x4 w; w.x = cvt_pk_bf16(a[0], a[1]); w.y = cvt_pk_bf16(a[2], a[3]); w.z = cvt_pk_bf16(b[0], b[1]); w.w = cvt_pk_bf16(b[2], b[3]); return w; }
;     __device__ __forceinline__ void operator()(const f32x4 (&acc)[2][2][4][2], const Unit& u, int wr, int wc, int fr, int fq) const {
;     ...
;                 for (int m = 0; m < 4; ++m) { if (m == 0) asm volatile("" ::: "memory"); const int row = row0 + ai * HALF + m * 16; const float rs = rstd_of(ssq, row);
;                     f32x4 v[2][2]; float ss = 0.f;
; #pragma unroll
;                     for (int bj = 0; bj < 2; ++bj)
; #pragma unroll
;                         for (int n = 0; n < 2; ++n) { v[bj][n] = acc[ai][bj][m][n] * rs; const f32x4 q = v[bj][n] * v[bj][n]; ss += (q[0] + q[1]) + (q[2] + q[3]); }
;                     ss += __shfl_xor(ss, 16); ss += __shfl_xor(ss, 32);
;                     const float rn = __builtin_amdgcn_rsqf(ss * (1.0f / 64.0f) + 1e-6f);
;                     f32x4 o[2][2];
; #pragma unroll
;                     for (int n = 0; n < 2; ++n) { const f32x4 c = *(const f32x4*)(cosT + (size_t)row * 32 + 8 * fq + 4 * n), s = *(const f32x4*)(sinT + (size_t)row * 32 + 8 * fq + 4 * n);
;                         const f32x4 y1 = v[0][n] * rn * gv[0][n], y2 = v[1][n] * rn * gv[1][n];
;                         o[0][n] = y1 * c - y2 * s; o[1][n] = y2 * c + y1 * s; }
;                     if (dok) {
; #pragma unroll
;                         for (int bj = 0; bj < 2; ++bj)
; #pragma unroll
;                             for (int n = 0; n < 2; ++n) cs[bj][n] = cs[bj][n] + o[bj][n]; }
; #pragma unroll
;                     for (int bj = 0; bj < 2; ++bj) *(u32x4*)(ob + (size_t)row * 2816 + 32 * bj) = pack8(o[bj][0] * osc, o[bj][1] * osc); }
.LBB0_431:
	v_mad_i64_i32 v[210:211], s[12:13], v186, s92, v[180:181]
	v_pk_mul_f32 v[186:187], v[114:115], v[192:193]
	v_pk_mul_f32 v[192:193], v[184:185], v[194:195]
	v_pk_mul_f32 v[200:201], v[114:115], v[200:201]
	v_cvt_pk_bf16_f32 v192, v192, v193
	v_cvt_pk_bf16_f32 v193, v186, v187
	v_pk_mul_f32 v[188:189], v[114:115], v[188:189]
	v_pk_mul_f32 v[186:187], v[184:185], v[190:191]
	v_pk_mul_f32 v[114:115], v[114:115], v[196:197]
	v_pk_mul_f32 v[194:195], v[184:185], v[202:203]
	v_pk_mul_f32 v[190:191], v[184:185], v[198:199]
	v_cvt_pk_bf16_f32 v186, v186, v187
	v_cvt_pk_bf16_f32 v187, v188, v189
	v_cvt_pk_bf16_f32 v189, v114, v115
	v_add_u32_e32 v114, 0xb0, v182
	v_cvt_pk_bf16_f32 v194, v194, v195
	v_cvt_pk_bf16_f32 v195, v200, v201
	v_cvt_pk_bf16_f32 v188, v190, v191
	v_ashrrev_i32_e32 v115, 31, v114
	flat_store_dwordx4 v[210:211], v[192:195]
	flat_store_dwordx4 v[210:211], v[186:189] offset:64
	s_and_b64 vcc, exec, s[10:11]
	s_nop 0
	v_lshl_add_u64 v[186:187], v[114:115], 4, s[18:19]
	flat_load_dwordx4 v[186:189], v[186:187]
	v_lshlrev_b64 v[250:251], 7, v[114:115]
	v_lshl_add_u64 v[246:247], v[170:171], 0, v[250:251]
	v_lshl_add_u64 v[250:251], v[172:173], 0, v[250:251]
	global_load_dwordx4 v[246:249], v[246:247], off
	global_load_dwordx4 v[250:253], v[250:251], off
	s_waitcnt vmcnt(2) lgkmcnt(0)
	v_mov_b32_e32 v190, v187
	v_mov_b32_e32 v191, v188
	v_mov_b32_e32 v187, v189
	v_pk_add_f32 v[186:187], v[190:191], v[186:187]
	s_nop 0
	v_add_f32_e32 v112, v186, v187
	v_fmamk_f32 v112, v112, 0x3a800000, v231
	v_rsq_f32_e32 v112, v112
	s_nop 0
	v_pk_mul_f32 v[202:203], v[12:13], v[112:113] op_sel_hi:[1,0]
	v_pk_mul_f32 v[210:211], v[14:15], v[112:113] op_sel_hi:[1,0]
	v_pk_mul_f32 v[188:189], v[202:203], v[202:203]
	v_pk_mul_f32 v[186:187], v[210:211], v[210:211]
	v_pk_mul_f32 v[212:213], v[4:5], v[112:113] op_sel_hi:[1,0]
	v_pk_mov_b32 v[190:191], v[188:189], v[186:187] op_sel:[1,0]
	v_mov_b32_e32 v189, v187
	v_pk_add_f32 v[186:187], v[190:191], v[188:189]
	v_pk_mul_f32 v[188:189], v[10:11], v[112:113] op_sel_hi:[1,0]
	v_pk_add_f32 v[194:195], v[186:187], v[186:187] op_sel_hi:[0,1]
	v_pk_mul_f32 v[186:187], v[8:9], v[112:113] op_sel_hi:[1,0]
	v_pk_mul_f32 v[190:191], v[188:189], v[188:189]
	v_pk_mul_f32 v[192:193], v[186:187], v[186:187]
	v_pk_mul_f32 v[224:225], v[6:7], v[112:113] op_sel_hi:[1,0]
	v_pk_mov_b32 v[196:197], v[192:193], v[190:191] op_sel:[1,0]
	v_mov_b32_e32 v193, v191
	v_pk_add_f32 v[190:191], v[196:197], v[192:193]
	v_pk_mul_f32 v[192:193], v[212:213], v[212:213]
	v_pk_add_f32 v[196:197], v[190:191], v[190:191] op_sel_hi:[0,1]
	v_pk_mul_f32 v[190:191], v[224:225], v[224:225]
	v_add_f32_e32 v199, v192, v193
	v_add_f32_e32 v201, v190, v191
	v_pk_mul_f32 v[190:191], v[0:1], v[112:113] op_sel_hi:[1,0]
	v_pk_mul_f32 v[192:193], v[2:3], v[112:113] op_sel_hi:[1,0]
	v_pk_mul_f32 v[228:229], v[190:191], v[190:191]
	v_pk_mul_f32 v[226:227], v[192:193], v[192:193]
	v_mov_b32_e32 v198, v228
	v_mov_b32_e32 v200, v229
	v_mov_b32_e32 v194, v226
	v_mov_b32_e32 v196, v227
	v_pk_add_f32 v[198:199], v[198:199], v[200:201]
	v_pk_add_f32 v[194:195], v[194:195], v[196:197]
	s_nop 0
	v_pk_add_f32 v[194:195], v[198:199], v[194:195]
	s_nop 0
	v_add_f32_e32 v112, v194, v195
	ds_bpermute_b32 v194, v209, v112
	s_waitcnt lgkmcnt(0)
	v_add_f32_e32 v112, v112, v194
	ds_bpermute_b32 v194, v222, v112
	s_waitcnt lgkmcnt(0)
	v_add_f32_e32 v112, v112, v194
	v_lshlrev_b64 v[194:195], 7, v[114:115]
	v_lshl_add_u64 v[222:223], v[170:171], 0, v[194:195]
	v_lshl_add_u64 v[226:227], v[172:173], 0, v[194:195]
	s_waitcnt vmcnt(0)
	v_mov_b64_e32 v[194:195], v[246:247]
	v_mov_b64_e32 v[196:197], v[248:249]
	v_mov_b64_e32 v[198:199], v[250:251]
	v_mov_b64_e32 v[200:201], v[252:253]
	v_fmamk_f32 v112, v112, 0x3c800000, v231
	v_rsq_f32_e32 v112, v112
	s_nop 0
	v_pk_mul_f32 v[202:203], v[202:203], v[112:113] op_sel_hi:[1,0]
	v_pk_mul_f32 v[210:211], v[210:211], v[112:113] op_sel_hi:[1,0]
	v_pk_mul_f32 v[202:203], v[144:145], v[202:203]
	v_pk_mul_f32 v[144:145], v[212:213], v[112:113] op_sel_hi:[1,0]
	v_pk_mul_f32 v[210:211], v[146:147], v[210:211]
	v_pk_mul_f32 v[146:147], v[224:225], v[112:113] op_sel_hi:[1,0]
	v_pk_mul_f32 v[140:141], v[140:141], v[144:145]
	v_pk_mul_f32 v[142:143], v[142:143], v[146:147]
	v_pk_mul_f32 v[188:189], v[188:189], v[112:113] op_sel_hi:[1,0]
	v_pk_mul_f32 v[186:187], v[186:187], v[112:113] op_sel_hi:[1,0]
	v_pk_mul_f32 v[188:189], v[138:139], v[188:189]
	v_pk_mul_f32 v[186:187], v[136:137], v[186:187]
	v_pk_mul_f32 v[136:137], v[190:191], v[112:113] op_sel_hi:[1,0]
	v_pk_mul_f32 v[138:139], v[192:193], v[112:113] op_sel_hi:[1,0]
	v_pk_mul_f32 v[132:133], v[132:133], v[136:137]
	v_pk_mul_f32 v[134:135], v[134:135], v[138:139]
	s_waitcnt vmcnt(0) lgkmcnt(0)
	v_pk_mul_f32 v[146:147], v[198:199], v[140:141]
	v_pk_mul_f32 v[144:145], v[200:201], v[142:143]
	v_pk_fma_f32 v[146:147], v[194:195], v[202:203], v[146:147] neg_lo:[0,0,1] neg_hi:[0,0,1]
	v_pk_mul_f32 v[194:195], v[194:195], v[140:141]
	v_pk_mul_f32 v[140:141], v[196:197], v[142:143]
	v_pk_fma_f32 v[144:145], v[196:197], v[210:211], v[144:145] neg_lo:[0,0,1] neg_hi:[0,0,1]
	v_pk_fma_f32 v[140:141], v[200:201], v[210:211], v[140:141]
	v_pk_fma_f32 v[142:143], v[198:199], v[202:203], v[194:195]
	flat_load_dwordx4 v[194:197], v[222:223] offset:16
	flat_load_dwordx4 v[198:201], v[226:227] offset:16
	s_waitcnt vmcnt(0) lgkmcnt(0)
	v_pk_mul_f32 v[190:191], v[194:195], v[132:133]
	v_pk_mul_f32 v[138:139], v[198:199], v[132:133]
	v_pk_mul_f32 v[136:137], v[200:201], v[134:135]
	v_pk_mul_f32 v[132:133], v[196:197], v[134:135]
	v_pk_fma_f32 v[136:137], v[196:197], v[188:189], v[136:137] neg_lo:[0,0,1] neg_hi:[0,0,1]
	v_pk_fma_f32 v[138:139], v[194:195], v[186:187], v[138:139] neg_lo:[0,0,1] neg_hi:[0,0,1]
	v_pk_fma_f32 v[132:133], v[200:201], v[188:189], v[132:133]
	v_pk_fma_f32 v[134:135], v[198:199], v[186:187], v[190:191]
	s_cbranch_vccnz .LBB0_433
	v_pk_add_f32 v[162:163], v[162:163], v[144:145]
	v_pk_add_f32 v[160:161], v[160:161], v[146:147]
	v_pk_add_f32 v[158:159], v[158:159], v[136:137]
	v_pk_add_f32 v[156:157], v[156:157], v[138:139]
	v_pk_add_f32 v[154:155], v[154:155], v[140:141]
	v_pk_add_f32 v[152:153], v[152:153], v[142:143]
	v_pk_add_f32 v[150:151], v[150:151], v[132:133]
	v_pk_add_f32 v[148:149], v[148:149], v[134:135]
